# v30 plus de-serialized attention Q-tile loads and combine gathers
# speedup vs baseline: 1.0031x; 1.0031x over previous
.LBB0_1428:
	s_ff1_i32_b32 s11, s12
	v_readlane_b32 s10, v154, s11
	s_lshl_b32 s11, s11, 3
	s_add_i32 s14, s11, s3
	s_ashr_i32 s15, s14, 31
	s_add_i32 s13, s12, -1
	s_ashr_i32 s11, s10, 31
	s_lshl_b64 s[14:15], s[14:15], 19
	s_add_u32 s14, s16, s14
	s_addc_u32 s15, s17, s15
	s_lshl_b64 s[10:11], s[10:11], 11
	s_add_u32 s10, s14, s10
	s_addc_u32 s11, s15, s11
	global_load_dwordx2 v[34:35], v155, s[10:11]
	global_load_dwordx2 v[160:161], v155, s[10:11] offset:512
	global_load_dwordx2 v[162:163], v155, s[10:11] offset:1024
	global_load_dwordx2 v[164:165], v155, s[10:11] offset:1536
	s_and_b32 s12, s13, s12
	s_cmp_lg_u32 s12, 0
	s_waitcnt vmcnt(3)
	v_lshlrev_b32_e32 v36, 16, v34
	v_and_b32_e32 v37, 0xffff0000, v34
	v_lshlrev_b32_e32 v34, 16, v35
	v_and_b32_e32 v35, 0xffff0000, v35
	v_pk_add_f32 v[130:131], v[130:131], v[34:35]
	v_pk_add_f32 v[138:139], v[138:139], v[36:37]
	s_waitcnt vmcnt(2)
	v_lshlrev_b32_e32 v36, 16, v160
	v_and_b32_e32 v37, 0xffff0000, v160
	v_lshlrev_b32_e32 v34, 16, v161
	v_and_b32_e32 v35, 0xffff0000, v161
	v_pk_add_f32 v[136:137], v[136:137], v[34:35]
	v_pk_add_f32 v[128:129], v[128:129], v[36:37]
	s_waitcnt vmcnt(1)
	v_lshlrev_b32_e32 v36, 16, v162
	v_and_b32_e32 v37, 0xffff0000, v162
	v_lshlrev_b32_e32 v34, 16, v163
	v_and_b32_e32 v35, 0xffff0000, v163
	v_pk_add_f32 v[134:135], v[134:135], v[34:35]
	v_pk_add_f32 v[126:127], v[126:127], v[36:37]
	s_waitcnt vmcnt(0)
	v_lshlrev_b32_e32 v36, 16, v164
	v_and_b32_e32 v37, 0xffff0000, v164
	v_lshlrev_b32_e32 v34, 16, v165
	v_and_b32_e32 v35, 0xffff0000, v165
	v_pk_add_f32 v[124:125], v[124:125], v[36:37]
	v_pk_add_f32 v[132:133], v[132:133], v[34:35]
	s_cbranch_scc1 .LBB0_1428

.LBB0_1446:
	s_ff1_i32_b32 s15, s11
	s_add_i32 s14, s15, 16
	s_lshl_b32 s15, s15, 3
	s_add_i32 s18, s15, s3
	v_readlane_b32 s14, v154, s14
	s_ashr_i32 s19, s18, 31
	s_add_i32 s20, s11, -1
	s_ashr_i32 s15, s14, 31
	s_lshl_b64 s[18:19], s[18:19], 19
	s_add_u32 s18, s16, s18
	s_addc_u32 s19, s17, s19
	s_lshl_b64 s[14:15], s[14:15], 11
	s_add_u32 s14, s18, s14
	s_addc_u32 s15, s19, s15
	global_load_dwordx2 v[34:35], v155, s[14:15]
	global_load_dwordx2 v[160:161], v155, s[14:15] offset:512
	global_load_dwordx2 v[162:163], v155, s[14:15] offset:1024
	global_load_dwordx2 v[164:165], v155, s[14:15] offset:1536
	s_and_b32 s11, s20, s11
	s_cmp_lg_u32 s11, 0
	s_waitcnt vmcnt(3)
	v_lshlrev_b32_e32 v36, 16, v34
	v_and_b32_e32 v37, 0xffff0000, v34
	v_lshlrev_b32_e32 v34, 16, v35
	v_and_b32_e32 v35, 0xffff0000, v35
	v_pk_add_f32 v[142:143], v[142:143], v[34:35]
	v_pk_add_f32 v[46:47], v[46:47], v[36:37]
	s_waitcnt vmcnt(2)
	v_lshlrev_b32_e32 v36, 16, v160
	v_and_b32_e32 v37, 0xffff0000, v160
	v_lshlrev_b32_e32 v34, 16, v161
	v_and_b32_e32 v35, 0xffff0000, v161
	v_pk_add_f32 v[140:141], v[140:141], v[34:35]
	v_pk_add_f32 v[42:43], v[42:43], v[36:37]
	s_waitcnt vmcnt(1)
	v_lshlrev_b32_e32 v36, 16, v162
	v_and_b32_e32 v37, 0xffff0000, v162
	v_lshlrev_b32_e32 v34, 16, v163
	v_and_b32_e32 v35, 0xffff0000, v163
	v_pk_add_f32 v[48:49], v[48:49], v[34:35]
	v_pk_add_f32 v[38:39], v[38:39], v[36:37]
	s_waitcnt vmcnt(0)
	v_lshlrev_b32_e32 v36, 16, v164
	v_and_b32_e32 v37, 0xffff0000, v164
	v_lshlrev_b32_e32 v34, 16, v165
	v_and_b32_e32 v35, 0xffff0000, v165
	v_pk_add_f32 v[40:41], v[40:41], v[36:37]
	v_pk_add_f32 v[44:45], v[44:45], v[34:35]
	s_cbranch_scc1 .LBB0_1446

.LBB0_1481:
	s_ff1_i32_b32 s13, s9
	s_or_b32 s12, s13, 32
	s_lshl_b32 s13, s13, 3
	s_add_i32 s14, s13, s3
	v_readlane_b32 s12, v154, s12
	s_ashr_i32 s15, s14, 31
	s_add_i32 s18, s9, -1
	s_ashr_i32 s13, s12, 31
	s_lshl_b64 s[14:15], s[14:15], 19
	s_add_u32 s14, s16, s14
	s_addc_u32 s15, s17, s15
	s_lshl_b64 s[12:13], s[12:13], 11
	s_add_u32 s12, s14, s12
	s_addc_u32 s13, s15, s13
	global_load_dwordx2 v[34:35], v155, s[12:13]
	global_load_dwordx2 v[160:161], v155, s[12:13] offset:512
	global_load_dwordx2 v[162:163], v155, s[12:13] offset:1024
	global_load_dwordx2 v[164:165], v155, s[12:13] offset:1536
	s_and_b32 s9, s18, s9
	s_cmp_lg_u32 s9, 0
	s_waitcnt vmcnt(3)
	v_lshlrev_b32_e32 v36, 16, v34
	v_and_b32_e32 v37, 0xffff0000, v34
	v_lshlrev_b32_e32 v34, 16, v35
	v_and_b32_e32 v35, 0xffff0000, v35
	v_pk_add_f32 v[138:139], v[138:139], v[34:35]
	v_pk_add_f32 v[130:131], v[130:131], v[36:37]
	s_waitcnt vmcnt(2)
	v_lshlrev_b32_e32 v36, 16, v160
	v_and_b32_e32 v37, 0xffff0000, v160
	v_lshlrev_b32_e32 v34, 16, v161
	v_and_b32_e32 v35, 0xffff0000, v161
	v_pk_add_f32 v[136:137], v[136:137], v[34:35]
	v_pk_add_f32 v[128:129], v[128:129], v[36:37]
	s_waitcnt vmcnt(1)
	v_lshlrev_b32_e32 v36, 16, v162
	v_and_b32_e32 v37, 0xffff0000, v162
	v_lshlrev_b32_e32 v34, 16, v163
	v_and_b32_e32 v35, 0xffff0000, v163
	v_pk_add_f32 v[134:135], v[134:135], v[34:35]
	v_pk_add_f32 v[124:125], v[124:125], v[36:37]
	s_waitcnt vmcnt(0)
	v_lshlrev_b32_e32 v36, 16, v164
	v_and_b32_e32 v37, 0xffff0000, v164
	v_lshlrev_b32_e32 v34, 16, v165
	v_and_b32_e32 v35, 0xffff0000, v165
	v_pk_add_f32 v[126:127], v[126:127], v[36:37]
	v_pk_add_f32 v[132:133], v[132:133], v[34:35]
	s_cbranch_scc1 .LBB0_1481

.LBB0_1499:
	s_ff1_i32_b32 s1, s9
	s_add_i32 s0, s1, 48
	s_lshl_b32 s1, s1, 3
	s_add_i32 s18, s1, s3
	v_readlane_b32 s0, v154, s0
	s_ashr_i32 s19, s18, 31
	s_add_i32 s13, s9, -1
	s_ashr_i32 s1, s0, 31
	s_lshl_b64 s[18:19], s[18:19], 19
	s_add_u32 s18, s16, s18
	s_addc_u32 s19, s17, s19
	s_lshl_b64 s[0:1], s[0:1], 11
	s_add_u32 s0, s18, s0
	s_addc_u32 s1, s19, s1
	global_load_dwordx2 v[34:35], v155, s[0:1]
	global_load_dwordx2 v[160:161], v155, s[0:1] offset:512
	global_load_dwordx2 v[162:163], v155, s[0:1] offset:1024
	global_load_dwordx2 v[164:165], v155, s[0:1] offset:1536
	s_and_b32 s9, s13, s9
	s_cmp_lg_u32 s9, 0
	s_waitcnt vmcnt(3)
	v_lshlrev_b32_e32 v36, 16, v34
	v_and_b32_e32 v37, 0xffff0000, v34
	v_lshlrev_b32_e32 v34, 16, v35
	v_and_b32_e32 v35, 0xffff0000, v35
	v_pk_add_f32 v[142:143], v[142:143], v[34:35]
	v_pk_add_f32 v[46:47], v[46:47], v[36:37]
	s_waitcnt vmcnt(2)
	v_lshlrev_b32_e32 v36, 16, v160
	v_and_b32_e32 v37, 0xffff0000, v160
	v_lshlrev_b32_e32 v34, 16, v161
	v_and_b32_e32 v35, 0xffff0000, v161
	v_pk_add_f32 v[140:141], v[140:141], v[34:35]
	v_pk_add_f32 v[42:43], v[42:43], v[36:37]
	s_waitcnt vmcnt(1)
	v_lshlrev_b32_e32 v36, 16, v162
	v_and_b32_e32 v37, 0xffff0000, v162
	v_lshlrev_b32_e32 v34, 16, v163
	v_and_b32_e32 v35, 0xffff0000, v163
	v_pk_add_f32 v[48:49], v[48:49], v[34:35]
	v_pk_add_f32 v[38:39], v[38:39], v[36:37]
	s_waitcnt vmcnt(0)
	v_lshlrev_b32_e32 v36, 16, v164
	v_and_b32_e32 v37, 0xffff0000, v164
	v_lshlrev_b32_e32 v34, 16, v165
	v_and_b32_e32 v35, 0xffff0000, v165
	v_pk_add_f32 v[40:41], v[40:41], v[36:37]
	v_pk_add_f32 v[44:45], v[44:45], v[34:35]
	s_cbranch_scc1 .LBB0_1499
